# adds: first sample-mLSTM copy requests all gate preacts, biases and m0 in one round trip (was four)
# baseline (speedup 1.0000x reference)
; __device__ __forceinline__ float logsigmoid_fast(float x) { return fminf(x, 0.f) - __logf(1.f + __expf(-fabsf(x))); }
; __device__ __forceinline__ void mlstm_sample_unit(const Frame& F, int b, int h) {
;     ...
;     float li[4], bcum[4], mt[4], at[4], gs[4], sm[4][4], den[4];
;     const float m0 = F.in[6][bh];
;     { float acc = 0.f;
; #pragma unroll
;       for (int t = 0; t < 4; ++t) { const float* gp = gates + (size_t)(SP + b * 4 + t) * 8; li[t] = gp[h] + F.in[15][h]; acc += logsigmoid_fast(gp[4 + h] + F.in[16][h]); bcum[t] = acc; } }
; #pragma unroll
;     for (int t = 0; t < 4; ++t) { const float mi = bcum[t] + m0; float m = mi;
; #pragma unroll
;         for (int s = 0; s < 4; ++s) if (s <= t) m = fmaxf(m, bcum[t] - bcum[s] + li[s]);
;         mt[t] = m; at[t] = __expf(mi - m); float dsum = at[t] * sS[16 + t];
; #pragma unroll
;         for (int s = 0; s < 4; ++s) { sm[t][s] = (s <= t) ? sS[t * 4 + s] * __expf(bcum[t] - bcum[s] + li[s] - m) : 0.f; dsum += sm[t][s]; }
;         den[t] = fmaxf(fabsf(dsum), __expf(-m)); }
.LBB0_373:
	s_or_b64 exec, exec, s[42:43]
	v_readlane_b32 s12, v245, 37
	s_add_i32 s62, s28, 0x2000
	s_lshl_b64 s[82:83], s[34:35], 2
	v_readlane_b32 s24, v245, 49
	v_readlane_b32 s25, v245, 50
	s_add_u32 s46, s24, s82
	s_addc_u32 s47, s25, s83
	s_lshl_b32 s29, s29, 2
	s_add_u32 s53, s95, s29
	s_addc_u32 s91, s96, 0
	s_ashr_i32 s63, s62, 31
	v_readlane_b32 s13, v245, 38
	v_readlane_b32 s14, v245, 39
	v_readlane_b32 s15, v245, 40
	v_readlane_b32 s16, v245, 41
	v_readlane_b32 s17, v245, 42
	v_readlane_b32 s18, v245, 43
	v_readlane_b32 s19, v245, 44
	v_readlane_b32 s20, v245, 45
	v_readlane_b32 s21, v245, 46
	v_readlane_b32 s22, v245, 47
	v_readlane_b32 s23, v245, 48
	v_readlane_b32 s26, v245, 51
	v_readlane_b32 s27, v245, 52
	s_lshl_b64 s[42:43], s[62:63], 5
	v_readlane_b32 s12, v245, 21
	s_add_u32 s48, s53, s42
	v_mov_b32_e32 v0, s29
	v_readlane_b32 s13, v245, 22
	s_addc_u32 s49, s91, s43
	s_waitcnt lgkmcnt(0)
	s_barrier
	v_readlane_b32 s26, v245, 17
	v_readlane_b32 s27, v245, 18
	global_load_dword v3, v1, s[48:49] offset:16
	global_load_dword v2, v0, s[12:13]
	global_load_dword v46, v1, s[48:49] offset:48
	global_load_dword v47, v1, s[48:49] offset:80
	global_load_dword v49, v1, s[48:49]
	global_load_dword v50, v1, s[48:49] offset:32
	global_load_dword v51, v1, s[48:49] offset:64
	global_load_dword v52, v1, s[48:49] offset:112
	global_load_dword v53, v1, s[48:49] offset:96
	global_load_dword v54, v1, s[46:47]
	global_load_dword v48, v0, s[26:27]
	v_readlane_b32 s14, v245, 23
	v_readlane_b32 s15, v245, 24
	v_readlane_b32 s16, v245, 25
	v_readlane_b32 s17, v245, 26
	v_readlane_b32 s18, v245, 27
	v_readlane_b32 s19, v245, 28
	v_readlane_b32 s20, v245, 29
	v_readlane_b32 s21, v245, 30
	v_readlane_b32 s22, v245, 31
	v_readlane_b32 s23, v245, 32
	v_readlane_b32 s24, v245, 33
	v_readlane_b32 s25, v245, 34
	v_readlane_b32 s26, v245, 35
	v_readlane_b32 s27, v245, 36
	v_readlane_b32 s12, v245, 3
	v_readlane_b32 s26, v245, 17
	v_readlane_b32 s27, v245, 18
	v_add_u32_e32 v161, 0x2000, v85
	v_add_u32_e32 v159, 0x2400, v85
	v_add_u32_e32 v158, 0x2800, v85
	v_add_u32_e32 v95, 0x2c00, v85
	v_readlane_b32 s13, v245, 4
	v_readlane_b32 s12, v245, 1
	v_readlane_b32 s13, v245, 2
	v_readlane_b32 s14, v245, 5
	v_readlane_b32 s15, v245, 6
	v_readlane_b32 s16, v245, 7
	v_readlane_b32 s17, v245, 8
	v_readlane_b32 s18, v245, 9
	v_readlane_b32 s19, v245, 10
	v_readlane_b32 s20, v245, 11
	v_readlane_b32 s21, v245, 12
	v_readlane_b32 s22, v245, 13
	v_readlane_b32 s23, v245, 14
	v_readlane_b32 s24, v245, 15
	v_readlane_b32 s25, v245, 16
	s_waitcnt vmcnt(0)
	v_add_f32_e32 v3, v2, v3
	v_mul_f32_e64 v4, |v3|, s30
	v_exp_f32_e32 v4, v4
	v_min_f32_e32 v3, 0, v3
	v_add_f32_e32 v18, 1.0, v4
	v_cmp_gt_f32_e32 vcc, s31, v18
	s_and_b64 s[42:43], vcc, exec
	s_cselect_b32 s29, 32, 0
	s_add_i32 s60, s28, 0x2001
	s_ashr_i32 s61, s60, 31
	s_lshl_b64 s[42:43], s[60:61], 5
	s_add_u32 s92, s53, s42
	s_addc_u32 s93, s91, s43
	v_mov_b32_e32 v4, v46
	v_cndmask_b32_e32 v21, 0, v133, vcc
	v_ldexp_f32 v18, v18, s29
	v_log_f32_e32 v33, v18
	s_waitcnt vmcnt(0)
	v_add_f32_e32 v22, v2, v4
	v_mul_f32_e64 v4, |v22|, s30
	v_exp_f32_e32 v4, v4
	v_mul_f32_e32 v34, 0x3f317217, v33
	v_fma_f32 v34, v33, s90, -v34
	v_fmac_f32_e32 v34, 0x3377d1cf, v33
	v_add_f32_e32 v23, 1.0, v4
	v_cmp_gt_f32_e32 vcc, s31, v23
	s_and_b64 s[42:43], vcc, exec
	s_cselect_b32 s42, 32, 0
	s_add_i32 s54, s28, 0x2002
	s_ashr_i32 s55, s54, 31
	v_cndmask_b32_e32 v24, 0, v133, vcc
	s_lshl_b64 vcc, s[54:55], 5
	s_add_u32 vcc_lo, s53, vcc_lo
	s_addc_u32 vcc_hi, s91, vcc_hi
	v_mov_b32_e32 v4, v47
	v_mov_b32_e32 v25, v48
	v_mov_b32_e32 v20, v49
	v_mov_b32_e32 v26, v50
	v_mov_b32_e32 v28, v51
	v_fmac_f32_e32 v34, 0x3f317217, v33
	v_min_f32_e32 v22, 0, v22
	s_waitcnt vmcnt(2)
	v_add_f32_e32 v20, v25, v20
	v_add_f32_e32 v27, v2, v4
	v_mul_f32_e64 v0, |v27|, s30
	v_exp_f32_e32 v0, v0
	s_nop 0
	v_add_f32_e32 v29, 1.0, v0
	v_cmp_gt_f32_e32 vcc, s31, v29
	s_and_b64 s[48:49], vcc, exec
	s_cselect_b32 s43, 32, 0
	s_add_i32 s48, s28, 0x2003
	s_ashr_i32 s49, s48, 31
	s_lshl_b64 s[92:93], s[48:49], 5
	s_add_u32 s92, s53, s92
	s_addc_u32 s93, s91, s93
	v_mov_b32_e32 v31, v52
	v_mov_b32_e32 v32, v53
	v_mov_b32_e32 v0, v54
	v_cndmask_b32_e32 v30, 0, v133, vcc
	v_cmp_lt_f32_e64 vcc, |v33|, s94
	ds_read2_b32 v[4:5], v161 offset1:8
	ds_read2_b32 v[6:7], v159 offset1:8
	ds_read2_b32 v[8:9], v158 offset1:8
	ds_read2_b32 v[16:17], v95 offset1:8
	ds_read2_b32 v[10:11], v161 offset0:16 offset1:24
	ds_read2_b32 v[12:13], v159 offset0:16 offset1:24
	ds_read2_b32 v[14:15], v158 offset0:16 offset1:24
	v_cndmask_b32_e32 v33, v33, v34, vcc
	v_sub_f32_e32 v21, v33, v21
	v_sub_f32_e32 v3, v3, v21
	v_ldexp_f32 v21, v23, s42
	v_log_f32_e32 v23, v21
	s_waitcnt vmcnt(4)
	v_add_f32_e32 v21, v25, v26
	v_add_f32_e32 v3, 0, v3
	ds_read2_b32 v[18:19], v95 offset0:16 offset1:24
	v_mul_f32_e32 v26, 0x3f317217, v23
	v_fma_f32 v26, v23, s90, -v26
	v_fmac_f32_e32 v26, 0x3377d1cf, v23
	v_fmac_f32_e32 v26, 0x3f317217, v23
	v_cmp_lt_f32_e64 vcc, |v23|, s94
	s_nop 1
	v_cndmask_b32_e32 v23, v23, v26, vcc
	v_sub_f32_e32 v23, v23, v24
	v_sub_f32_e32 v22, v22, v23
	v_ldexp_f32 v23, v29, s43
	v_log_f32_e32 v24, v23
	s_waitcnt vmcnt(3)
; __device__ __forceinline__ void mlstm_sample_unit(const Frame& F, int b, int h) {
;     ...
;     for (int t = 0; t < 4; ++t) { const float mi = bcum[t] + m0; float m = mi;
; #pragma unroll
;         for (int s = 0; s < 4; ++s) if (s <= t) m = fmaxf(m, bcum[t] - bcum[s] + li[s]);
;         mt[t] = m; at[t] = __expf(mi - m); float dsum = at[t] * sS[16 + t];
; #pragma unroll
;         for (int s = 0; s < 4; ++s) { sm[t][s] = (s <= t) ? sS[t * 4 + s] * __expf(bcum[t] - bcum[s] + li[s] - m) : 0.f; dsum += sm[t][s]; }
;         den[t] = fmaxf(fabsf(dsum), __expf(-m)); }
;     const float mnew = mt[3], decay = __expf(bcum[3] + m0 - mnew);
; #pragma unroll
;     for (int s = 0; s < 4; ++s) gs[s] = __expf(bcum[3] - bcum[s] + li[s] - mnew);
;     const int r8 = lane >> 3, seg = lane & 7, w = F.wave;
;     const float* c0b = F.in[4] + (size_t)bh * 65536 + (size_t)(w * 32 + r8) * 256 + seg * 4;
;     float* c1b = F.out + O_CS + (size_t)bh * 65536 + (size_t)(w * 32 + r8) * 256 + seg * 4;
;     float acc[4][4], gv[4][4];
; #pragma unroll
;     for (int rg = 0; rg < 4; ++rg)
; #pragma unroll
;         for (int t = 0; t < 4; ++t) { acc[rg][t] = 0.f; gv[rg][t] = gs[t] * sv[t * 256 + w * 32 + rg * 8 + r8]; }
;     if (tid == 0) {
; #pragma unroll
;         for (int t = 0; t < 4; ++t) { sS[40 + t] = at[t]; sS[44 + t] = den[t];
; #pragma unroll
;             for (int s2 = 0; s2 < 4; ++s2) sS[48 + t * 4 + s2] = sm[t][s2]; } }
	v_add_f32_e32 v23, v25, v28
	v_min_f32_e32 v26, 0, v27
	v_add_f32_e32 v22, v3, v22
	v_mul_f32_e32 v27, 0x3f317217, v24
	v_fma_f32 v27, v24, s90, -v27
	v_fmac_f32_e32 v27, 0x3377d1cf, v24
	v_fmac_f32_e32 v27, 0x3f317217, v24
	v_cmp_lt_f32_e64 vcc, |v24|, s94
	s_waitcnt vmcnt(2)
	v_add_f32_e32 v28, v2, v31
	v_mul_f32_e64 v2, |v28|, s30
	v_exp_f32_e32 v2, v2
	v_cndmask_b32_e32 v24, v24, v27, vcc
	v_sub_f32_e32 v24, v24, v30
	v_sub_f32_e32 v24, v26, v24
	v_add_f32_e32 v2, 1.0, v2
	v_cmp_gt_f32_e32 vcc, s31, v2
	s_and_b64 s[28:29], vcc, exec
	s_cselect_b32 s28, 32, 0
	v_ldexp_f32 v2, v2, s28
	v_log_f32_e32 v27, v2
	v_add_f32_e32 v2, v22, v24
	s_waitcnt vmcnt(1)
	v_add_f32_e32 v24, v25, v32
	v_min_f32_e32 v25, 0, v28
	v_mul_f32_e32 v28, 0x3f317217, v27
	v_fma_f32 v28, v27, s90, -v28
	v_fmac_f32_e32 v28, 0x3377d1cf, v27
	v_cndmask_b32_e32 v26, 0, v133, vcc
	v_fmac_f32_e32 v28, 0x3f317217, v27
	v_cmp_lt_f32_e64 vcc, |v27|, s94
	s_nop 1
	v_cndmask_b32_e32 v27, v27, v28, vcc
	v_sub_f32_e32 v26, v27, v26
	v_sub_f32_e32 v25, v25, v26
	v_add_f32_e32 v25, v2, v25
	v_sub_f32_e32 v27, v25, v3
	v_sub_f32_e32 v28, v25, v22
	s_waitcnt vmcnt(0)
	v_add_f32_e32 v26, v0, v25
	v_sub_f32_e32 v29, v25, v2
	v_sub_f32_e32 v25, v25, v25
	v_add_f32_e32 v27, v20, v27
	v_add_f32_e32 v28, v21, v28
	v_add_f32_e32 v29, v23, v29
	v_add_f32_e32 v24, v24, v25
	v_max3_f32 v25, v26, v27, v28
	v_max3_f32 v157, v25, v29, v24
	v_sub_f32_e32 v25, v26, v157
	v_sub_f32_e32 v24, v24, v157
	v_sub_f32_e32 v26, v27, v157
	v_sub_f32_e32 v27, v28, v157
	v_sub_f32_e32 v28, v29, v157
	v_mul_f32_e32 v25, 0x3fb8aa3b, v25
	v_mul_f32_e32 v24, 0x3fb8aa3b, v24
	v_mul_f32_e32 v26, 0x3fb8aa3b, v26
	v_mul_f32_e32 v27, 0x3fb8aa3b, v27
	v_mul_f32_e32 v28, 0x3fb8aa3b, v28
	v_exp_f32_e32 v100, v25
	v_exp_f32_e32 v99, v24
	v_exp_f32_e32 v102, v26
	v_exp_f32_e32 v103, v27
	v_exp_f32_e32 v98, v28
	s_and_saveexec_b64 s[46:47], s[12:13]
	s_cbranch_execz .LBB0_375
	v_sub_f32_e32 v25, v2, v3
	v_add_f32_e32 v24, v0, v2
	v_add_f32_e32 v25, v20, v25
	v_sub_f32_e32 v27, v2, v22
	v_sub_f32_e32 v2, v2, v2
	v_max_f32_e32 v26, v24, v25
	v_add_f32_e32 v27, v21, v27
	v_add_f32_e32 v2, v23, v2
	v_max3_f32 v23, v26, v27, v2
	v_sub_f32_e32 v25, v25, v23
	v_mul_f32_e32 v25, 0x3fb8aa3b, v25
	v_sub_f32_e32 v2, v2, v23
	v_exp_f32_e32 v34, v25
	v_sub_f32_e32 v25, v27, v23
	v_mul_f32_e32 v2, 0x3fb8aa3b, v2
	v_mul_f32_e32 v25, 0x3fb8aa3b, v25
	v_exp_f32_e32 v45, v2
	v_mul_f32_e32 v2, 0xbfb8aa3b, v23
	v_sub_f32_e32 v24, v24, v23
	v_exp_f32_e32 v35, v25
	v_exp_f32_e32 v25, v2
	v_add_f32_e32 v2, v0, v22
	v_sub_f32_e32 v23, v22, v3
	v_sub_f32_e32 v22, v22, v22
	v_add_f32_e32 v40, v20, v23
	v_add_f32_e32 v21, v21, v22
	v_max3_f32 v22, v2, v40, v21
	v_sub_f32_e32 v2, v2, v22
	v_mul_f32_e32 v2, 0x3fb8aa3b, v2
	v_add_f32_e32 v0, v0, v3
	v_sub_f32_e32 v3, v3, v3
	v_exp_f32_e32 v23, v2
	v_sub_f32_e32 v2, v40, v22
	v_add_f32_e32 v3, v20, v3
	v_mul_f32_e32 v2, 0x3fb8aa3b, v2
	v_max_f32_e32 v20, v0, v3
	v_exp_f32_e32 v40, v2
	v_sub_f32_e32 v2, v21, v22
	v_sub_f32_e32 v0, v0, v20
	v_mul_f32_e32 v2, 0x3fb8aa3b, v2
	v_mul_f32_e32 v0, 0x3fb8aa3b, v0
	v_exp_f32_e32 v41, v2
	v_mul_f32_e32 v2, 0xbfb8aa3b, v22
	v_exp_f32_e32 v22, v0
	v_sub_f32_e32 v0, v3, v20
	v_mul_f32_e32 v0, 0x3fb8aa3b, v0
	v_exp_f32_e32 v0, v0
	ds_read_b32 v37, v1 offset:12288
	ds_read_b64 v[38:39], v1 offset:12304
	ds_read_b96 v[42:44], v1 offset:12320
	ds_read_b128 v[26:29], v1 offset:12352
	ds_read_b128 v[30:33], v1 offset:12336
	v_mul_f32_e32 v3, 0xbfb8aa3b, v20
	v_exp_f32_e32 v3, v3
	s_waitcnt lgkmcnt(4)
	v_mul_f32_e32 v0, v0, v37
	v_mul_f32_e32 v24, 0x3fb8aa3b, v24
	v_exp_f32_e32 v20, v2
	s_waitcnt lgkmcnt(1)
	v_fma_f32 v2, v22, v26, v0
	v_exp_f32_e32 v24, v24
	v_max_f32_e64 v26, |v2|, v3
	v_mul_f32_e32 v2, 0xbfb8aa3b, v157
	v_exp_f32_e32 v46, v2
	v_mov_b32_e32 v2, v1
	v_mov_b32_e32 v3, v1
	v_pk_mul_f32 v[38:39], v[40:41], v[38:39]
	ds_write_b128 v1, v[0:3] offset:12480
	v_fma_f32 v0, v23, v27, v38
	v_add_f32_e32 v0, v0, v39
	v_pk_mul_f32 v[34:35], v[34:35], v[42:43]
	v_max_f32_e64 v27, |v0|, v20
	v_fma_f32 v0, v24, v28, v34
	v_add_f32_e32 v0, v0, v35
	v_fmac_f32_e32 v0, v45, v44
	s_waitcnt lgkmcnt(1)
	v_pk_mul_f32 v[20:21], v[102:103], v[30:31]
	v_max_f32_e64 v28, |v0|, v25
	v_mov_b32_e32 v25, v100
	v_fma_f32 v0, v100, v29, v20
	ds_write_b128 v1, v[22:25] offset:12448
	v_add_f32_e32 v0, v0, v21
	v_pk_mul_f32 v[22:23], v[98:99], v[32:33]
	v_mul_f32_e32 v36, v45, v44
	v_add_f32_e32 v0, v0, v22
	v_add_f32_e32 v0, v23, v0
	v_mov_b32_e32 v40, v1
	v_mov_b32_e32 v41, v1
	v_mov_b32_e32 v37, v1
	v_max_f32_e64 v29, |v0|, v46
	ds_write_b128 v1, v[38:41] offset:12496
	ds_write_b128 v1, v[34:37] offset:12512
	ds_write_b128 v1, v[26:29] offset:12464
	ds_write_b128 v1, v[20:23] offset:12528
